# GEMM1 K-loops: per-phase s_setprio toggling around the MFMA clusters removed (static default priority)
# speedup vs baseline: 1.0106x; 1.0106x over previous
.LBB0_151:
	ds_read_b128 v[130:133], v169
	ds_read_b128 v[134:137], v169 offset:1024
	ds_read_b128 v[138:141], v169 offset:2048
	ds_read_b128 v[142:145], v169 offset:3072
	s_add_u32 s57, s58, 0xfffc0080
	s_addc_u32 s60, s59, -1
	s_cmp_eq_u32 s55, 12
	s_cselect_b32 s63, s11, s60
	s_cselect_b32 s62, s10, s57
	s_cselect_b32 s61, s9, s3
	s_cselect_b32 s60, s8, s2
	v_lshl_add_u64 v[200:201], s[58:59], 0, v[160:161]
	s_add_i32 m0, s70, 0xc000
	ds_read_b128 v[164:167], v170
	ds_read_b128 v[172:175], v170 offset:1024
	ds_read_b128 v[176:179], v170 offset:2048
	ds_read_b128 v[180:183], v170 offset:3072
	ds_read_b128 v[184:187], v170 offset:4096
	ds_read_b128 v[188:191], v170 offset:5120
	ds_read_b128 v[192:195], v170 offset:6144
	ds_read_b128 v[196:199], v170 offset:7168
	global_load_lds_dwordx4 v[200:201], off
	v_lshl_add_u64 v[200:201], s[58:59], 0, v[162:163]
	s_add_i32 m0, s70, 0xe000
	s_nop 0
	global_load_lds_dwordx4 v[200:201], off
	s_waitcnt lgkmcnt(8)
	s_barrier
	s_waitcnt lgkmcnt(0)
	s_waitcnt lgkmcnt(0)
	v_mfma_f32_16x16x32_bf16 v[126:129], v[130:133], v[164:167], v[126:129]
	v_mfma_f32_16x16x32_bf16 v[122:125], v[138:141], v[164:167], v[122:125]
	v_mfma_f32_16x16x32_bf16 v[114:117], v[130:133], v[176:179], v[114:117]
	v_mfma_f32_16x16x32_bf16 v[106:109], v[138:141], v[176:179], v[106:109]
	v_mfma_f32_16x16x32_bf16 v[98:101], v[130:133], v[184:187], v[98:101]
	v_mfma_f32_16x16x32_bf16 v[90:93], v[138:141], v[184:187], v[90:93]
	v_mfma_f32_16x16x32_bf16 v[82:85], v[130:133], v[192:195], v[82:85]
	v_mfma_f32_16x16x32_bf16 v[74:77], v[138:141], v[192:195], v[74:77]
	v_mfma_f32_16x16x32_bf16 v[126:129], v[134:137], v[172:175], v[126:129]
	v_mfma_f32_16x16x32_bf16 v[122:125], v[142:145], v[172:175], v[122:125]
	v_mfma_f32_16x16x32_bf16 v[114:117], v[134:137], v[180:183], v[114:117]
	v_mfma_f32_16x16x32_bf16 v[106:109], v[142:145], v[180:183], v[106:109]
	v_mfma_f32_16x16x32_bf16 v[98:101], v[134:137], v[188:191], v[98:101]
	v_mfma_f32_16x16x32_bf16 v[90:93], v[142:145], v[188:191], v[90:93]
	v_mfma_f32_16x16x32_bf16 v[82:85], v[134:137], v[196:199], v[82:85]
	v_mfma_f32_16x16x32_bf16 v[74:77], v[142:145], v[196:199], v[74:77]
	s_barrier
	s_add_i32 s57, s96, s69
	v_lshl_add_u64 v[216:217], s[60:61], 0, v[152:153]
	s_mov_b32 m0, s57
	ds_read_b128 v[200:203], v171
	ds_read_b128 v[204:207], v171 offset:1024
	ds_read_b128 v[208:211], v171 offset:2048
	ds_read_b128 v[212:215], v171 offset:3072
	global_load_lds_dwordx4 v[216:217], off
	v_lshl_add_u64 v[218:219], s[60:61], 0, v[156:157]
	s_add_i32 m0, s57, 0x2000
	s_nop 0
	global_load_lds_dwordx4 v[218:219], off
	s_barrier
	s_waitcnt lgkmcnt(0)
	s_waitcnt lgkmcnt(0)
	v_mfma_f32_16x16x32_bf16 v[118:121], v[200:203], v[164:167], v[118:121]
	v_mfma_f32_16x16x32_bf16 v[110:113], v[208:211], v[164:167], v[110:113]
	v_mfma_f32_16x16x32_bf16 v[102:105], v[200:203], v[176:179], v[102:105]
	v_mfma_f32_16x16x32_bf16 v[94:97], v[208:211], v[176:179], v[94:97]
	v_mfma_f32_16x16x32_bf16 v[86:89], v[200:203], v[184:187], v[86:89]
	v_mfma_f32_16x16x32_bf16 v[78:81], v[208:211], v[184:187], v[78:81]
	v_mfma_f32_16x16x32_bf16 v[70:73], v[200:203], v[192:195], v[70:73]
	v_mfma_f32_16x16x32_bf16 v[66:69], v[208:211], v[192:195], v[66:69]
	v_mfma_f32_16x16x32_bf16 v[118:121], v[204:207], v[172:175], v[118:121]
	v_mfma_f32_16x16x32_bf16 v[110:113], v[212:215], v[172:175], v[110:113]
	v_mfma_f32_16x16x32_bf16 v[102:105], v[204:207], v[180:183], v[102:105]
	v_mfma_f32_16x16x32_bf16 v[94:97], v[212:215], v[180:183], v[94:97]
	v_mfma_f32_16x16x32_bf16 v[86:89], v[204:207], v[188:191], v[86:89]
	v_mfma_f32_16x16x32_bf16 v[78:81], v[212:215], v[188:191], v[78:81]
	v_mfma_f32_16x16x32_bf16 v[70:73], v[204:207], v[196:199], v[70:73]
	v_mfma_f32_16x16x32_bf16 v[66:69], v[212:215], v[196:199], v[66:69]
	s_mov_b32 m0, s70
	v_lshl_add_u64 v[220:221], s[62:63], 0, v[150:151]
	s_barrier
	ds_read_b128 v[164:167], v170 offset:16384
	ds_read_b128 v[172:175], v170 offset:17408
	ds_read_b128 v[176:179], v170 offset:18432
	ds_read_b128 v[180:183], v170 offset:19456
	ds_read_b128 v[184:187], v170 offset:20480
	ds_read_b128 v[188:191], v170 offset:21504
	ds_read_b128 v[192:195], v170 offset:22528
	ds_read_b128 v[196:199], v170 offset:23552
	global_load_lds_dwordx4 v[220:221], off
	v_lshl_add_u64 v[222:223], s[62:63], 0, v[154:155]
	s_mov_b32 m0, s71
	s_nop 0
	global_load_lds_dwordx4 v[222:223], off
	s_barrier
	s_waitcnt lgkmcnt(0)
	s_waitcnt lgkmcnt(0)
	v_mfma_f32_16x16x32_bf16 v[62:65], v[130:133], v[164:167], v[62:65]
	v_mfma_f32_16x16x32_bf16 v[58:61], v[138:141], v[164:167], v[58:61]
	v_mfma_f32_16x16x32_bf16 v[50:53], v[130:133], v[176:179], v[50:53]
	v_mfma_f32_16x16x32_bf16 v[42:45], v[138:141], v[176:179], v[42:45]
	v_mfma_f32_16x16x32_bf16 v[34:37], v[130:133], v[184:187], v[34:37]
	v_mfma_f32_16x16x32_bf16 v[26:29], v[138:141], v[184:187], v[26:29]
	v_mfma_f32_16x16x32_bf16 v[18:21], v[130:133], v[192:195], v[18:21]
	v_mfma_f32_16x16x32_bf16 v[10:13], v[138:141], v[192:195], v[10:13]
	v_mfma_f32_16x16x32_bf16 v[62:65], v[134:137], v[172:175], v[62:65]
	v_mfma_f32_16x16x32_bf16 v[58:61], v[142:145], v[172:175], v[58:61]
	v_mfma_f32_16x16x32_bf16 v[50:53], v[134:137], v[180:183], v[50:53]
	v_mfma_f32_16x16x32_bf16 v[42:45], v[142:145], v[180:183], v[42:45]
	v_mfma_f32_16x16x32_bf16 v[34:37], v[134:137], v[188:191], v[34:37]
	v_mfma_f32_16x16x32_bf16 v[26:29], v[142:145], v[188:191], v[26:29]
	v_mfma_f32_16x16x32_bf16 v[18:21], v[134:137], v[196:199], v[18:21]
	v_mfma_f32_16x16x32_bf16 v[10:13], v[142:145], v[196:199], v[10:13]
	s_barrier
	s_add_u32 s64, s60, 0x40000
	s_addc_u32 s65, s61, 0
	s_add_i32 s57, s33, s69
	v_lshl_add_u64 v[130:131], s[64:65], 0, v[152:153]
	s_mov_b32 m0, s57
	s_nop 0
	global_load_lds_dwordx4 v[130:131], off
	v_lshl_add_u64 v[130:131], s[64:65], 0, v[156:157]
	s_add_i32 m0, s57, 0x2000
	s_nop 0
	global_load_lds_dwordx4 v[130:131], off
	s_waitcnt vmcnt(6)
	s_barrier
	v_mfma_f32_16x16x32_bf16 v[54:57], v[200:203], v[164:167], v[54:57]
	v_mfma_f32_16x16x32_bf16 v[46:49], v[208:211], v[164:167], v[46:49]
	v_mfma_f32_16x16x32_bf16 v[38:41], v[200:203], v[176:179], v[38:41]
	v_mfma_f32_16x16x32_bf16 v[30:33], v[208:211], v[176:179], v[30:33]
	v_mfma_f32_16x16x32_bf16 v[22:25], v[200:203], v[184:187], v[22:25]
	v_mfma_f32_16x16x32_bf16 v[14:17], v[208:211], v[184:187], v[14:17]
	v_mfma_f32_16x16x32_bf16 v[6:9], v[200:203], v[192:195], v[6:9]
	v_mfma_f32_16x16x32_bf16 v[2:5], v[208:211], v[192:195], v[2:5]
	v_mfma_f32_16x16x32_bf16 v[54:57], v[204:207], v[172:175], v[54:57]
	v_mfma_f32_16x16x32_bf16 v[46:49], v[212:215], v[172:175], v[46:49]
	v_mfma_f32_16x16x32_bf16 v[38:41], v[204:207], v[180:183], v[38:41]
	v_mfma_f32_16x16x32_bf16 v[30:33], v[212:215], v[180:183], v[30:33]
	v_mfma_f32_16x16x32_bf16 v[22:25], v[204:207], v[188:191], v[22:25]
	v_mfma_f32_16x16x32_bf16 v[14:17], v[212:215], v[188:191], v[14:17]
	v_mfma_f32_16x16x32_bf16 v[6:9], v[204:207], v[196:199], v[6:9]
	v_mfma_f32_16x16x32_bf16 v[2:5], v[212:215], v[196:199], v[2:5]
	s_add_i32 s57, 0, 0x18000
	v_add_u32_e32 v142, s57, v149
	s_barrier
	ds_read_b128 v[130:133], v142
	ds_read_b128 v[134:137], v142 offset:1024
	ds_read_b128 v[138:141], v142 offset:2048
	ds_read_b128 v[142:145], v142 offset:3072
	s_add_u32 s62, s62, 0x40000
	s_addc_u32 s63, s63, 0
	s_mov_b32 m0, s72
	v_lshl_add_u64 v[200:201], s[62:63], 0, v[150:151]
	ds_read_b128 v[164:167], v170 offset:32768
	ds_read_b128 v[172:175], v170 offset:33792
	ds_read_b128 v[176:179], v170 offset:34816
	ds_read_b128 v[180:183], v170 offset:35840
	ds_read_b128 v[184:187], v170 offset:36864
	ds_read_b128 v[188:191], v170 offset:37888
	ds_read_b128 v[192:195], v170 offset:38912
	ds_read_b128 v[196:199], v170 offset:39936
	global_load_lds_dwordx4 v[200:201], off
	v_lshl_add_u64 v[200:201], s[62:63], 0, v[154:155]
	s_mov_b32 m0, s73
	s_nop 0
	global_load_lds_dwordx4 v[200:201], off
	s_waitcnt lgkmcnt(8)
	s_barrier
	s_waitcnt lgkmcnt(0)
	s_waitcnt lgkmcnt(0)
	v_mfma_f32_16x16x32_bf16 v[126:129], v[130:133], v[164:167], v[126:129]
	v_mfma_f32_16x16x32_bf16 v[122:125], v[138:141], v[164:167], v[122:125]
	v_mfma_f32_16x16x32_bf16 v[114:117], v[130:133], v[176:179], v[114:117]
	v_mfma_f32_16x16x32_bf16 v[106:109], v[138:141], v[176:179], v[106:109]
	v_mfma_f32_16x16x32_bf16 v[98:101], v[130:133], v[184:187], v[98:101]
	v_mfma_f32_16x16x32_bf16 v[90:93], v[138:141], v[184:187], v[90:93]
	v_mfma_f32_16x16x32_bf16 v[82:85], v[130:133], v[192:195], v[82:85]
	v_mfma_f32_16x16x32_bf16 v[74:77], v[138:141], v[192:195], v[74:77]
	v_mfma_f32_16x16x32_bf16 v[126:129], v[134:137], v[172:175], v[126:129]
	v_mfma_f32_16x16x32_bf16 v[122:125], v[142:145], v[172:175], v[122:125]
	v_mfma_f32_16x16x32_bf16 v[114:117], v[134:137], v[180:183], v[114:117]
	v_mfma_f32_16x16x32_bf16 v[106:109], v[142:145], v[180:183], v[106:109]
	v_mfma_f32_16x16x32_bf16 v[98:101], v[134:137], v[188:191], v[98:101]
	v_mfma_f32_16x16x32_bf16 v[90:93], v[142:145], v[188:191], v[90:93]
	v_mfma_f32_16x16x32_bf16 v[82:85], v[134:137], v[196:199], v[82:85]
	v_mfma_f32_16x16x32_bf16 v[74:77], v[142:145], v[196:199], v[74:77]
	s_barrier
	s_add_i32 s62, 0, 0x1c000
	s_add_i32 s57, s57, s69
	v_add_u32_e32 v158, s62, v149
	v_lshl_add_u64 v[216:217], v[216:217], 0, s[0:1]
	s_mov_b32 m0, s57
	ds_read_b128 v[200:203], v158
	ds_read_b128 v[204:207], v158 offset:1024
	ds_read_b128 v[208:211], v158 offset:2048
	ds_read_b128 v[212:215], v158 offset:3072
	global_load_lds_dwordx4 v[216:217], off
	v_lshl_add_u64 v[216:217], v[218:219], 0, s[0:1]
	s_add_i32 m0, s57, 0x2000
	s_nop 0
	global_load_lds_dwordx4 v[216:217], off
	s_barrier
	s_waitcnt lgkmcnt(0)
	s_waitcnt lgkmcnt(0)
	v_mfma_f32_16x16x32_bf16 v[118:121], v[200:203], v[164:167], v[118:121]
	v_mfma_f32_16x16x32_bf16 v[110:113], v[208:211], v[164:167], v[110:113]
	v_mfma_f32_16x16x32_bf16 v[102:105], v[200:203], v[176:179], v[102:105]
	v_mfma_f32_16x16x32_bf16 v[94:97], v[208:211], v[176:179], v[94:97]
	v_mfma_f32_16x16x32_bf16 v[86:89], v[200:203], v[184:187], v[86:89]
	v_mfma_f32_16x16x32_bf16 v[78:81], v[208:211], v[184:187], v[78:81]
	v_mfma_f32_16x16x32_bf16 v[70:73], v[200:203], v[192:195], v[70:73]
	v_mfma_f32_16x16x32_bf16 v[66:69], v[208:211], v[192:195], v[66:69]
	v_mfma_f32_16x16x32_bf16 v[118:121], v[204:207], v[172:175], v[118:121]
	v_mfma_f32_16x16x32_bf16 v[110:113], v[212:215], v[172:175], v[110:113]
	v_mfma_f32_16x16x32_bf16 v[102:105], v[204:207], v[180:183], v[102:105]
	v_mfma_f32_16x16x32_bf16 v[94:97], v[212:215], v[180:183], v[94:97]
	v_mfma_f32_16x16x32_bf16 v[86:89], v[204:207], v[188:191], v[86:89]
	v_mfma_f32_16x16x32_bf16 v[78:81], v[212:215], v[188:191], v[78:81]
	v_mfma_f32_16x16x32_bf16 v[70:73], v[204:207], v[196:199], v[70:73]
	v_mfma_f32_16x16x32_bf16 v[66:69], v[212:215], v[196:199], v[66:69]
	s_mov_b32 m0, s90
	v_lshl_add_u64 v[216:217], v[220:221], 0, s[0:1]
	s_barrier
	ds_read_b128 v[164:167], v170 offset:49152
	ds_read_b128 v[172:175], v170 offset:50176
	ds_read_b128 v[176:179], v170 offset:51200
	ds_read_b128 v[180:183], v170 offset:52224
	ds_read_b128 v[184:187], v170 offset:53248
	ds_read_b128 v[188:191], v170 offset:54272
	ds_read_b128 v[192:195], v170 offset:55296
	ds_read_b128 v[196:199], v170 offset:56320
	global_load_lds_dwordx4 v[216:217], off
	v_lshl_add_u64 v[216:217], v[222:223], 0, s[0:1]
	s_mov_b32 m0, s91
	s_nop 0
	global_load_lds_dwordx4 v[216:217], off
	s_barrier
	s_waitcnt lgkmcnt(0)
	s_waitcnt lgkmcnt(0)
	v_mfma_f32_16x16x32_bf16 v[62:65], v[130:133], v[164:167], v[62:65]
	v_mfma_f32_16x16x32_bf16 v[58:61], v[138:141], v[164:167], v[58:61]
	v_mfma_f32_16x16x32_bf16 v[50:53], v[130:133], v[176:179], v[50:53]
	v_mfma_f32_16x16x32_bf16 v[42:45], v[138:141], v[176:179], v[42:45]
	v_mfma_f32_16x16x32_bf16 v[34:37], v[130:133], v[184:187], v[34:37]
	v_mfma_f32_16x16x32_bf16 v[26:29], v[138:141], v[184:187], v[26:29]
	v_mfma_f32_16x16x32_bf16 v[18:21], v[130:133], v[192:195], v[18:21]
	v_mfma_f32_16x16x32_bf16 v[10:13], v[138:141], v[192:195], v[10:13]
	v_mfma_f32_16x16x32_bf16 v[62:65], v[134:137], v[172:175], v[62:65]
	v_mfma_f32_16x16x32_bf16 v[58:61], v[142:145], v[172:175], v[58:61]
	v_mfma_f32_16x16x32_bf16 v[50:53], v[134:137], v[180:183], v[50:53]
	v_mfma_f32_16x16x32_bf16 v[42:45], v[142:145], v[180:183], v[42:45]
	v_mfma_f32_16x16x32_bf16 v[34:37], v[134:137], v[188:191], v[34:37]
	v_mfma_f32_16x16x32_bf16 v[26:29], v[142:145], v[188:191], v[26:29]
	v_mfma_f32_16x16x32_bf16 v[18:21], v[134:137], v[196:199], v[18:21]
	v_mfma_f32_16x16x32_bf16 v[10:13], v[142:145], v[196:199], v[10:13]
	s_barrier
	s_add_u32 s60, s60, 0x40080
	s_addc_u32 s61, s61, 0
	s_add_i32 s57, s62, s69
	v_lshl_add_u64 v[130:131], s[60:61], 0, v[152:153]
	s_mov_b32 m0, s57
	s_nop 0
	global_load_lds_dwordx4 v[130:131], off
	v_lshl_add_u64 v[130:131], s[60:61], 0, v[156:157]
	s_add_i32 m0, s57, 0x2000
	s_nop 0
	global_load_lds_dwordx4 v[130:131], off
	s_waitcnt vmcnt(6)
	s_barrier
	v_mfma_f32_16x16x32_bf16 v[54:57], v[200:203], v[164:167], v[54:57]
	v_mfma_f32_16x16x32_bf16 v[46:49], v[208:211], v[164:167], v[46:49]
	v_mfma_f32_16x16x32_bf16 v[38:41], v[200:203], v[176:179], v[38:41]
	v_mfma_f32_16x16x32_bf16 v[30:33], v[208:211], v[176:179], v[30:33]
	v_mfma_f32_16x16x32_bf16 v[22:25], v[200:203], v[184:187], v[22:25]
	v_mfma_f32_16x16x32_bf16 v[14:17], v[208:211], v[184:187], v[14:17]
	v_mfma_f32_16x16x32_bf16 v[6:9], v[200:203], v[192:195], v[6:9]
	v_mfma_f32_16x16x32_bf16 v[2:5], v[208:211], v[192:195], v[2:5]
	v_mfma_f32_16x16x32_bf16 v[54:57], v[204:207], v[172:175], v[54:57]
	v_mfma_f32_16x16x32_bf16 v[46:49], v[212:215], v[172:175], v[46:49]
	v_mfma_f32_16x16x32_bf16 v[38:41], v[204:207], v[180:183], v[38:41]
	v_mfma_f32_16x16x32_bf16 v[30:33], v[212:215], v[180:183], v[30:33]
	v_mfma_f32_16x16x32_bf16 v[22:25], v[204:207], v[188:191], v[22:25]
	v_mfma_f32_16x16x32_bf16 v[14:17], v[212:215], v[188:191], v[14:17]
	v_mfma_f32_16x16x32_bf16 v[6:9], v[204:207], v[196:199], v[6:9]
	v_mfma_f32_16x16x32_bf16 v[2:5], v[212:215], v[196:199], v[2:5]
	s_add_i32 s55, s55, 2
	s_add_u32 s58, s58, 0x100
	s_addc_u32 s59, s59, 0
	s_add_u32 s2, s2, 0x100
	s_addc_u32 s3, s3, 0
	s_cmp_gt_u32 s55, 13
	s_barrier
	s_cbranch_scc0 .LBB0_151
	v_mov_b32_e32 v130, v147
	v_mov_b32_e32 v173, v1
	s_ashr_i32 s55, s19, 1
	s_mov_b64 s[62:63], -1
	v_lshlrev_b32_e32 v174, 3, v130
	s_mov_b64 s[60:61], 0
	s_cmp_lt_i32 s55, 4
	s_mov_b64 s[58:59], 0
	s_cbranch_scc1 .LBB0_167
	s_cmp_gt_i32 s55, 5
	s_cbranch_scc0 .LBB0_161
	s_cmp_gt_i32 s55, 6
	s_cbranch_scc0 .LBB0_158
	s_cmp_eq_u32 s55, 7
	s_mov_b64 s[58:59], -1
	s_cbranch_scc0 .LBB0_157
	s_lshl_b32 s2, s18, 8
	s_or_b32 s2, s2, s85
	v_add_u32_e32 v140, s2, v174
	s_lshl_b32 s2, s19, 8
	v_ashrrev_i32_e32 v130, 3, v140
	s_and_b32 s2, s2, 0x100
	v_and_b32_e32 v130, 0xfffffe00, v130
	s_add_i32 s2, s2, s84
	v_add3_u32 v134, s2, v173, v130
	v_ashrrev_i32_e32 v135, 31, v134
	v_lshlrev_b64 v[136:137], 13, v[134:135]
	v_and_b32_e32 v135, 0xff8, v140
	v_lshl_add_u64 v[136:137], s[14:15], 0, v[136:137]
	v_lshlrev_b32_e32 v158, 1, v135
	v_cvt_pk_bf16_f32 v130, v126, v127
	v_cvt_pk_bf16_f32 v131, v128, v129
	v_cvt_pk_bf16_f32 v132, v122, v123
	v_cvt_pk_bf16_f32 v133, v124, v125
	v_lshl_add_u64 v[138:139], v[136:137], 0, v[158:159]
	global_store_dwordx4 v[138:139], v[130:133], off
	v_mov_b32_e32 v139, v159
	s_mov_b64 s[58:59], 0
	v_add_u32_e32 v130, 0x80, v140
	v_and_b32_e32 v135, 0xff8, v130
	v_lshlrev_b32_e32 v138, 1, v135
	v_cvt_pk_bf16_f32 v130, v118, v119
	v_cvt_pk_bf16_f32 v131, v120, v121
	v_cvt_pk_bf16_f32 v132, v110, v111
	v_cvt_pk_bf16_f32 v133, v112, v113
	v_lshl_add_u64 v[136:137], v[136:137], 0, v[138:139]
	global_store_dwordx4 v[136:137], v[130:133], off
	s_nop 1
	v_add_u32_e32 v130, 16, v134
	v_ashrrev_i32_e32 v131, 31, v130
	v_lshlrev_b64 v[136:137], 13, v[130:131]
	v_lshl_add_u64 v[136:137], s[14:15], 0, v[136:137]
	v_cvt_pk_bf16_f32 v130, v114, v115
	v_cvt_pk_bf16_f32 v131, v116, v117
	v_cvt_pk_bf16_f32 v132, v106, v107
	v_cvt_pk_bf16_f32 v133, v108, v109
	v_lshl_add_u64 v[140:141], v[136:137], 0, v[158:159]
	global_store_dwordx4 v[140:141], v[130:133], off
	v_lshl_add_u64 v[136:137], v[136:137], 0, v[138:139]
	s_nop 0
	v_cvt_pk_bf16_f32 v130, v102, v103
	v_cvt_pk_bf16_f32 v131, v104, v105
	v_cvt_pk_bf16_f32 v132, v94, v95
	v_cvt_pk_bf16_f32 v133, v96, v97
	global_store_dwordx4 v[136:137], v[130:133], off
	s_nop 1
	v_add_u32_e32 v130, 32, v134
	v_ashrrev_i32_e32 v131, 31, v130
	v_lshlrev_b64 v[136:137], 13, v[130:131]
	v_lshl_add_u64 v[136:137], s[14:15], 0, v[136:137]
	v_cvt_pk_bf16_f32 v130, v98, v99
	v_cvt_pk_bf16_f32 v131, v100, v101
	v_cvt_pk_bf16_f32 v132, v90, v91
	v_cvt_pk_bf16_f32 v133, v92, v93
	v_lshl_add_u64 v[140:141], v[136:137], 0, v[158:159]
	global_store_dwordx4 v[140:141], v[130:133], off
	v_lshl_add_u64 v[136:137], v[136:137], 0, v[138:139]
	s_nop 0
	v_cvt_pk_bf16_f32 v130, v86, v87
	v_cvt_pk_bf16_f32 v131, v88, v89
	v_cvt_pk_bf16_f32 v132, v78, v79
	v_cvt_pk_bf16_f32 v133, v80, v81
	global_store_dwordx4 v[136:137], v[130:133], off
	s_nop 1
	v_add_u32_e32 v130, 48, v134
	v_ashrrev_i32_e32 v131, 31, v130
	v_lshlrev_b64 v[136:137], 13, v[130:131]
	v_lshl_add_u64 v[136:137], s[14:15], 0, v[136:137]
	v_cvt_pk_bf16_f32 v130, v82, v83
	v_cvt_pk_bf16_f32 v131, v84, v85
	v_cvt_pk_bf16_f32 v132, v74, v75
	v_cvt_pk_bf16_f32 v133, v76, v77
	v_lshl_add_u64 v[140:141], v[136:137], 0, v[158:159]
	global_store_dwordx4 v[140:141], v[130:133], off
	v_lshl_add_u64 v[136:137], v[136:137], 0, v[138:139]
	s_nop 0
	v_cvt_pk_bf16_f32 v130, v70, v71
	v_cvt_pk_bf16_f32 v131, v72, v73
	v_cvt_pk_bf16_f32 v132, v66, v67
	v_cvt_pk_bf16_f32 v133, v68, v69
	global_store_dwordx4 v[136:137], v[130:133], off
	s_nop 1
	v_add_u32_e32 v130, 0x80, v134
	v_ashrrev_i32_e32 v131, 31, v130
	v_lshlrev_b64 v[136:137], 13, v[130:131]
	v_lshl_add_u64 v[136:137], s[14:15], 0, v[136:137]
	v_cvt_pk_bf16_f32 v130, v62, v63
	v_cvt_pk_bf16_f32 v131, v64, v65
	v_cvt_pk_bf16_f32 v132, v58, v59
	v_cvt_pk_bf16_f32 v133, v60, v61
	v_lshl_add_u64 v[140:141], v[136:137], 0, v[158:159]
	global_store_dwordx4 v[140:141], v[130:133], off
	v_lshl_add_u64 v[136:137], v[136:137], 0, v[138:139]
	s_nop 0
	v_cvt_pk_bf16_f32 v130, v54, v55
	v_cvt_pk_bf16_f32 v131, v56, v57
	v_cvt_pk_bf16_f32 v132, v46, v47
	v_cvt_pk_bf16_f32 v133, v48, v49
	global_store_dwordx4 v[136:137], v[130:133], off
	s_nop 1
	v_add_u32_e32 v130, 0x90, v134
	v_ashrrev_i32_e32 v131, 31, v130
	v_lshlrev_b64 v[136:137], 13, v[130:131]
	v_lshl_add_u64 v[136:137], s[14:15], 0, v[136:137]
	v_cvt_pk_bf16_f32 v130, v50, v51
	v_cvt_pk_bf16_f32 v131, v52, v53
	v_cvt_pk_bf16_f32 v132, v42, v43
	v_cvt_pk_bf16_f32 v133, v44, v45
	v_lshl_add_u64 v[140:141], v[136:137], 0, v[158:159]
	global_store_dwordx4 v[140:141], v[130:133], off
	v_lshl_add_u64 v[136:137], v[136:137], 0, v[138:139]
	s_nop 0
	v_cvt_pk_bf16_f32 v130, v38, v39
	v_cvt_pk_bf16_f32 v131, v40, v41
	v_cvt_pk_bf16_f32 v132, v30, v31
	v_cvt_pk_bf16_f32 v133, v32, v33
	global_store_dwordx4 v[136:137], v[130:133], off
	s_nop 1
	v_add_u32_e32 v130, 0xa0, v134
	v_ashrrev_i32_e32 v131, 31, v130
	v_lshlrev_b64 v[136:137], 13, v[130:131]
	v_lshl_add_u64 v[136:137], s[14:15], 0, v[136:137]
	v_cvt_pk_bf16_f32 v130, v34, v35
	v_cvt_pk_bf16_f32 v131, v36, v37
	v_cvt_pk_bf16_f32 v132, v26, v27
	v_cvt_pk_bf16_f32 v133, v28, v29
	v_lshl_add_u64 v[140:141], v[136:137], 0, v[158:159]
	global_store_dwordx4 v[140:141], v[130:133], off
	v_lshl_add_u64 v[136:137], v[136:137], 0, v[138:139]
	s_nop 0
	v_cvt_pk_bf16_f32 v130, v22, v23
	v_cvt_pk_bf16_f32 v131, v24, v25
	v_cvt_pk_bf16_f32 v132, v14, v15
	v_cvt_pk_bf16_f32 v133, v16, v17
	global_store_dwordx4 v[136:137], v[130:133], off
	s_nop 1
	v_add_u32_e32 v130, 0xb0, v134
	v_ashrrev_i32_e32 v131, 31, v130
	v_lshlrev_b64 v[134:135], 13, v[130:131]
	v_lshl_add_u64 v[134:135], s[14:15], 0, v[134:135]
	v_cvt_pk_bf16_f32 v130, v18, v19
	v_cvt_pk_bf16_f32 v131, v20, v21
	v_cvt_pk_bf16_f32 v132, v10, v11
	v_cvt_pk_bf16_f32 v133, v12, v13
	v_lshl_add_u64 v[136:137], v[134:135], 0, v[158:159]
	global_store_dwordx4 v[136:137], v[130:133], off
	v_lshl_add_u64 v[134:135], v[134:135], 0, v[138:139]
	s_nop 0
	v_cvt_pk_bf16_f32 v130, v6, v7
	v_cvt_pk_bf16_f32 v131, v8, v9
	v_cvt_pk_bf16_f32 v132, v2, v3
	v_cvt_pk_bf16_f32 v133, v4, v5
	global_store_dwordx4 v[134:135], v[130:133], off

.LBB0_281:
	ds_read_b128 v[130:133], v167
	ds_read_b128 v[134:137], v167 offset:1024
	ds_read_b128 v[138:141], v167 offset:2048
	ds_read_b128 v[142:145], v167 offset:3072
	s_add_u32 s43, s44, 0xfffc0080
	s_addc_u32 s46, s45, -1
	s_cmp_eq_u32 s41, 12
	s_cselect_b32 s49, s9, s46
	s_cselect_b32 s48, s8, s43
	s_cselect_b32 s47, s7, s3
	s_cselect_b32 s46, s6, s2
	v_lshl_add_u64 v[200:201], s[44:45], 0, v[158:159]
	s_add_i32 m0, s53, 0xc000
	ds_read_b128 v[162:165], v169
	ds_read_b128 v[172:175], v169 offset:1024
	ds_read_b128 v[176:179], v169 offset:2048
	ds_read_b128 v[180:183], v169 offset:3072
	ds_read_b128 v[184:187], v169 offset:4096
	ds_read_b128 v[188:191], v169 offset:5120
	ds_read_b128 v[192:195], v169 offset:6144
	ds_read_b128 v[196:199], v169 offset:7168
	global_load_lds_dwordx4 v[200:201], off
	v_lshl_add_u64 v[200:201], s[44:45], 0, v[160:161]
	s_add_i32 m0, s53, 0xe000
	s_nop 0
	global_load_lds_dwordx4 v[200:201], off
	s_waitcnt lgkmcnt(8)
	s_barrier
	s_waitcnt lgkmcnt(0)
	s_waitcnt lgkmcnt(0)
	v_mfma_f32_16x16x32_bf16 v[126:129], v[130:133], v[162:165], v[126:129]
	v_mfma_f32_16x16x32_bf16 v[122:125], v[138:141], v[162:165], v[122:125]
	v_mfma_f32_16x16x32_bf16 v[114:117], v[130:133], v[176:179], v[114:117]
	v_mfma_f32_16x16x32_bf16 v[106:109], v[138:141], v[176:179], v[106:109]
	v_mfma_f32_16x16x32_bf16 v[98:101], v[130:133], v[184:187], v[98:101]
	v_mfma_f32_16x16x32_bf16 v[90:93], v[138:141], v[184:187], v[90:93]
	v_mfma_f32_16x16x32_bf16 v[82:85], v[130:133], v[192:195], v[82:85]
	v_mfma_f32_16x16x32_bf16 v[74:77], v[138:141], v[192:195], v[74:77]
	v_mfma_f32_16x16x32_bf16 v[126:129], v[134:137], v[172:175], v[126:129]
	v_mfma_f32_16x16x32_bf16 v[122:125], v[142:145], v[172:175], v[122:125]
	v_mfma_f32_16x16x32_bf16 v[114:117], v[134:137], v[180:183], v[114:117]
	v_mfma_f32_16x16x32_bf16 v[106:109], v[142:145], v[180:183], v[106:109]
	v_mfma_f32_16x16x32_bf16 v[98:101], v[134:137], v[188:191], v[98:101]
	v_mfma_f32_16x16x32_bf16 v[90:93], v[142:145], v[188:191], v[90:93]
	v_mfma_f32_16x16x32_bf16 v[82:85], v[134:137], v[196:199], v[82:85]
	v_mfma_f32_16x16x32_bf16 v[74:77], v[142:145], v[196:199], v[74:77]
	s_barrier
	s_add_i32 s43, s67, s52
	v_lshl_add_u64 v[216:217], s[46:47], 0, v[150:151]
	s_mov_b32 m0, s43
	ds_read_b128 v[200:203], v170
	ds_read_b128 v[204:207], v170 offset:1024
	ds_read_b128 v[208:211], v170 offset:2048
	ds_read_b128 v[212:215], v170 offset:3072
	global_load_lds_dwordx4 v[216:217], off
	v_lshl_add_u64 v[218:219], s[46:47], 0, v[154:155]
	s_add_i32 m0, s43, 0x2000
	s_nop 0
	global_load_lds_dwordx4 v[218:219], off
	s_barrier
	s_waitcnt lgkmcnt(0)
	s_waitcnt lgkmcnt(0)
	v_mfma_f32_16x16x32_bf16 v[118:121], v[200:203], v[162:165], v[118:121]
	v_mfma_f32_16x16x32_bf16 v[110:113], v[208:211], v[162:165], v[110:113]
	v_mfma_f32_16x16x32_bf16 v[102:105], v[200:203], v[176:179], v[102:105]
	v_mfma_f32_16x16x32_bf16 v[94:97], v[208:211], v[176:179], v[94:97]
	v_mfma_f32_16x16x32_bf16 v[86:89], v[200:203], v[184:187], v[86:89]
	v_mfma_f32_16x16x32_bf16 v[78:81], v[208:211], v[184:187], v[78:81]
	v_mfma_f32_16x16x32_bf16 v[70:73], v[200:203], v[192:195], v[70:73]
	v_mfma_f32_16x16x32_bf16 v[66:69], v[208:211], v[192:195], v[66:69]
	v_mfma_f32_16x16x32_bf16 v[118:121], v[204:207], v[172:175], v[118:121]
	v_mfma_f32_16x16x32_bf16 v[110:113], v[212:215], v[172:175], v[110:113]
	v_mfma_f32_16x16x32_bf16 v[102:105], v[204:207], v[180:183], v[102:105]
	v_mfma_f32_16x16x32_bf16 v[94:97], v[212:215], v[180:183], v[94:97]
	v_mfma_f32_16x16x32_bf16 v[86:89], v[204:207], v[188:191], v[86:89]
	v_mfma_f32_16x16x32_bf16 v[78:81], v[212:215], v[188:191], v[78:81]
	v_mfma_f32_16x16x32_bf16 v[70:73], v[204:207], v[196:199], v[70:73]
	v_mfma_f32_16x16x32_bf16 v[66:69], v[212:215], v[196:199], v[66:69]
	s_mov_b32 m0, s53
	v_lshl_add_u64 v[220:221], s[48:49], 0, v[148:149]
	s_barrier
	ds_read_b128 v[162:165], v169 offset:16384
	ds_read_b128 v[172:175], v169 offset:17408
	ds_read_b128 v[176:179], v169 offset:18432
	ds_read_b128 v[180:183], v169 offset:19456
	ds_read_b128 v[184:187], v169 offset:20480
	ds_read_b128 v[188:191], v169 offset:21504
	ds_read_b128 v[192:195], v169 offset:22528
	ds_read_b128 v[196:199], v169 offset:23552
	global_load_lds_dwordx4 v[220:221], off
	v_lshl_add_u64 v[222:223], s[48:49], 0, v[152:153]
	s_mov_b32 m0, s54
	s_nop 0
	global_load_lds_dwordx4 v[222:223], off
	s_barrier
	s_waitcnt lgkmcnt(0)
	s_waitcnt lgkmcnt(0)
	v_mfma_f32_16x16x32_bf16 v[62:65], v[130:133], v[162:165], v[62:65]
	v_mfma_f32_16x16x32_bf16 v[58:61], v[138:141], v[162:165], v[58:61]
	v_mfma_f32_16x16x32_bf16 v[50:53], v[130:133], v[176:179], v[50:53]
	v_mfma_f32_16x16x32_bf16 v[42:45], v[138:141], v[176:179], v[42:45]
	v_mfma_f32_16x16x32_bf16 v[34:37], v[130:133], v[184:187], v[34:37]
	v_mfma_f32_16x16x32_bf16 v[26:29], v[138:141], v[184:187], v[26:29]
	v_mfma_f32_16x16x32_bf16 v[18:21], v[130:133], v[192:195], v[18:21]
	v_mfma_f32_16x16x32_bf16 v[10:13], v[138:141], v[192:195], v[10:13]
	v_mfma_f32_16x16x32_bf16 v[62:65], v[134:137], v[172:175], v[62:65]
	v_mfma_f32_16x16x32_bf16 v[58:61], v[142:145], v[172:175], v[58:61]
	v_mfma_f32_16x16x32_bf16 v[50:53], v[134:137], v[180:183], v[50:53]
	v_mfma_f32_16x16x32_bf16 v[42:45], v[142:145], v[180:183], v[42:45]
	v_mfma_f32_16x16x32_bf16 v[34:37], v[134:137], v[188:191], v[34:37]
	v_mfma_f32_16x16x32_bf16 v[26:29], v[142:145], v[188:191], v[26:29]
	v_mfma_f32_16x16x32_bf16 v[18:21], v[134:137], v[196:199], v[18:21]
	v_mfma_f32_16x16x32_bf16 v[10:13], v[142:145], v[196:199], v[10:13]
	s_barrier
	s_add_u32 s50, s46, 0x40000
	s_addc_u32 s51, s47, 0
	s_add_i32 s43, s68, s52
	v_lshl_add_u64 v[130:131], s[50:51], 0, v[150:151]
	s_mov_b32 m0, s43
	s_nop 0
	global_load_lds_dwordx4 v[130:131], off
	v_lshl_add_u64 v[130:131], s[50:51], 0, v[154:155]
	s_add_i32 m0, s43, 0x2000
	s_nop 0
	global_load_lds_dwordx4 v[130:131], off
	s_waitcnt vmcnt(6)
	s_barrier
	v_mfma_f32_16x16x32_bf16 v[54:57], v[200:203], v[162:165], v[54:57]
	v_mfma_f32_16x16x32_bf16 v[46:49], v[208:211], v[162:165], v[46:49]
	v_mfma_f32_16x16x32_bf16 v[38:41], v[200:203], v[176:179], v[38:41]
	v_mfma_f32_16x16x32_bf16 v[30:33], v[208:211], v[176:179], v[30:33]
	v_mfma_f32_16x16x32_bf16 v[22:25], v[200:203], v[184:187], v[22:25]
	v_mfma_f32_16x16x32_bf16 v[14:17], v[208:211], v[184:187], v[14:17]
	v_mfma_f32_16x16x32_bf16 v[6:9], v[200:203], v[192:195], v[6:9]
	v_mfma_f32_16x16x32_bf16 v[2:5], v[208:211], v[192:195], v[2:5]
	v_mfma_f32_16x16x32_bf16 v[54:57], v[204:207], v[172:175], v[54:57]
	v_mfma_f32_16x16x32_bf16 v[46:49], v[212:215], v[172:175], v[46:49]
	v_mfma_f32_16x16x32_bf16 v[38:41], v[204:207], v[180:183], v[38:41]
	v_mfma_f32_16x16x32_bf16 v[30:33], v[212:215], v[180:183], v[30:33]
	v_mfma_f32_16x16x32_bf16 v[22:25], v[204:207], v[188:191], v[22:25]
	v_mfma_f32_16x16x32_bf16 v[14:17], v[212:215], v[188:191], v[14:17]
	v_mfma_f32_16x16x32_bf16 v[6:9], v[204:207], v[196:199], v[6:9]
	v_mfma_f32_16x16x32_bf16 v[2:5], v[212:215], v[196:199], v[2:5]
	s_add_i32 s43, 0, 0x18000
	v_add_u32_e32 v142, s43, v166
	s_barrier
	ds_read_b128 v[130:133], v142
	ds_read_b128 v[134:137], v142 offset:1024
	ds_read_b128 v[138:141], v142 offset:2048
	ds_read_b128 v[142:145], v142 offset:3072
	s_add_u32 s48, s48, 0x40000
	s_addc_u32 s49, s49, 0
	s_mov_b32 m0, s55
	v_lshl_add_u64 v[200:201], s[48:49], 0, v[148:149]
	ds_read_b128 v[162:165], v169 offset:32768
	ds_read_b128 v[172:175], v169 offset:33792
	ds_read_b128 v[176:179], v169 offset:34816
	ds_read_b128 v[180:183], v169 offset:35840
	ds_read_b128 v[184:187], v169 offset:36864
	ds_read_b128 v[188:191], v169 offset:37888
	ds_read_b128 v[192:195], v169 offset:38912
	ds_read_b128 v[196:199], v169 offset:39936
	global_load_lds_dwordx4 v[200:201], off
	v_lshl_add_u64 v[200:201], s[48:49], 0, v[152:153]
	s_mov_b32 m0, s56
	s_nop 0
	global_load_lds_dwordx4 v[200:201], off
	s_waitcnt lgkmcnt(8)
	s_barrier
	s_waitcnt lgkmcnt(0)
	s_waitcnt lgkmcnt(0)
	v_mfma_f32_16x16x32_bf16 v[126:129], v[130:133], v[162:165], v[126:129]
	v_mfma_f32_16x16x32_bf16 v[122:125], v[138:141], v[162:165], v[122:125]
	v_mfma_f32_16x16x32_bf16 v[114:117], v[130:133], v[176:179], v[114:117]
	v_mfma_f32_16x16x32_bf16 v[106:109], v[138:141], v[176:179], v[106:109]
	v_mfma_f32_16x16x32_bf16 v[98:101], v[130:133], v[184:187], v[98:101]
	v_mfma_f32_16x16x32_bf16 v[90:93], v[138:141], v[184:187], v[90:93]
	v_mfma_f32_16x16x32_bf16 v[82:85], v[130:133], v[192:195], v[82:85]
	v_mfma_f32_16x16x32_bf16 v[74:77], v[138:141], v[192:195], v[74:77]
	v_mfma_f32_16x16x32_bf16 v[126:129], v[134:137], v[172:175], v[126:129]
	v_mfma_f32_16x16x32_bf16 v[122:125], v[142:145], v[172:175], v[122:125]
	v_mfma_f32_16x16x32_bf16 v[114:117], v[134:137], v[180:183], v[114:117]
	v_mfma_f32_16x16x32_bf16 v[106:109], v[142:145], v[180:183], v[106:109]
	v_mfma_f32_16x16x32_bf16 v[98:101], v[134:137], v[188:191], v[98:101]
	v_mfma_f32_16x16x32_bf16 v[90:93], v[142:145], v[188:191], v[90:93]
	v_mfma_f32_16x16x32_bf16 v[82:85], v[134:137], v[196:199], v[82:85]
	v_mfma_f32_16x16x32_bf16 v[74:77], v[142:145], v[196:199], v[74:77]
	s_barrier
	s_add_i32 s48, 0, 0x1c000
	s_add_i32 s43, s43, s52
	v_add_u32_e32 v156, s48, v166
	v_lshl_add_u64 v[216:217], v[216:217], 0, s[10:11]
	s_mov_b32 m0, s43
	ds_read_b128 v[200:203], v156
	ds_read_b128 v[204:207], v156 offset:1024
	ds_read_b128 v[208:211], v156 offset:2048
	ds_read_b128 v[212:215], v156 offset:3072
	global_load_lds_dwordx4 v[216:217], off
	v_lshl_add_u64 v[216:217], v[218:219], 0, s[10:11]
	s_add_i32 m0, s43, 0x2000
	s_nop 0
	global_load_lds_dwordx4 v[216:217], off
	s_barrier
	s_waitcnt lgkmcnt(0)
	s_waitcnt lgkmcnt(0)
	v_mfma_f32_16x16x32_bf16 v[118:121], v[200:203], v[162:165], v[118:121]
	v_mfma_f32_16x16x32_bf16 v[110:113], v[208:211], v[162:165], v[110:113]
	v_mfma_f32_16x16x32_bf16 v[102:105], v[200:203], v[176:179], v[102:105]
	v_mfma_f32_16x16x32_bf16 v[94:97], v[208:211], v[176:179], v[94:97]
	v_mfma_f32_16x16x32_bf16 v[86:89], v[200:203], v[184:187], v[86:89]
	v_mfma_f32_16x16x32_bf16 v[78:81], v[208:211], v[184:187], v[78:81]
	v_mfma_f32_16x16x32_bf16 v[70:73], v[200:203], v[192:195], v[70:73]
	v_mfma_f32_16x16x32_bf16 v[66:69], v[208:211], v[192:195], v[66:69]
	v_mfma_f32_16x16x32_bf16 v[118:121], v[204:207], v[172:175], v[118:121]
	v_mfma_f32_16x16x32_bf16 v[110:113], v[212:215], v[172:175], v[110:113]
	v_mfma_f32_16x16x32_bf16 v[102:105], v[204:207], v[180:183], v[102:105]
	v_mfma_f32_16x16x32_bf16 v[94:97], v[212:215], v[180:183], v[94:97]
	v_mfma_f32_16x16x32_bf16 v[86:89], v[204:207], v[188:191], v[86:89]
	v_mfma_f32_16x16x32_bf16 v[78:81], v[212:215], v[188:191], v[78:81]
	v_mfma_f32_16x16x32_bf16 v[70:73], v[204:207], v[196:199], v[70:73]
	v_mfma_f32_16x16x32_bf16 v[66:69], v[212:215], v[196:199], v[66:69]
	s_mov_b32 m0, s60
	v_lshl_add_u64 v[216:217], v[220:221], 0, s[10:11]
	s_barrier
	ds_read_b128 v[162:165], v169 offset:49152
	ds_read_b128 v[172:175], v169 offset:50176
	ds_read_b128 v[176:179], v169 offset:51200
	ds_read_b128 v[180:183], v169 offset:52224
	ds_read_b128 v[184:187], v169 offset:53248
	ds_read_b128 v[188:191], v169 offset:54272
	ds_read_b128 v[192:195], v169 offset:55296
	ds_read_b128 v[196:199], v169 offset:56320
	global_load_lds_dwordx4 v[216:217], off
	v_lshl_add_u64 v[216:217], v[222:223], 0, s[10:11]
	s_mov_b32 m0, s61
	s_nop 0
	global_load_lds_dwordx4 v[216:217], off
	s_barrier
	s_waitcnt lgkmcnt(0)
	s_waitcnt lgkmcnt(0)
	v_mfma_f32_16x16x32_bf16 v[62:65], v[130:133], v[162:165], v[62:65]
	v_mfma_f32_16x16x32_bf16 v[58:61], v[138:141], v[162:165], v[58:61]
	v_mfma_f32_16x16x32_bf16 v[50:53], v[130:133], v[176:179], v[50:53]
	v_mfma_f32_16x16x32_bf16 v[42:45], v[138:141], v[176:179], v[42:45]
	v_mfma_f32_16x16x32_bf16 v[34:37], v[130:133], v[184:187], v[34:37]
	v_mfma_f32_16x16x32_bf16 v[26:29], v[138:141], v[184:187], v[26:29]
	v_mfma_f32_16x16x32_bf16 v[18:21], v[130:133], v[192:195], v[18:21]
	v_mfma_f32_16x16x32_bf16 v[10:13], v[138:141], v[192:195], v[10:13]
	v_mfma_f32_16x16x32_bf16 v[62:65], v[134:137], v[172:175], v[62:65]
	v_mfma_f32_16x16x32_bf16 v[58:61], v[142:145], v[172:175], v[58:61]
	v_mfma_f32_16x16x32_bf16 v[50:53], v[134:137], v[180:183], v[50:53]
	v_mfma_f32_16x16x32_bf16 v[42:45], v[142:145], v[180:183], v[42:45]
	v_mfma_f32_16x16x32_bf16 v[34:37], v[134:137], v[188:191], v[34:37]
	v_mfma_f32_16x16x32_bf16 v[26:29], v[142:145], v[188:191], v[26:29]
	v_mfma_f32_16x16x32_bf16 v[18:21], v[134:137], v[196:199], v[18:21]
	v_mfma_f32_16x16x32_bf16 v[10:13], v[142:145], v[196:199], v[10:13]
	s_barrier
	s_add_u32 s46, s46, 0x40080
	s_addc_u32 s47, s47, 0
	s_add_i32 s43, s48, s52
	v_lshl_add_u64 v[130:131], s[46:47], 0, v[150:151]
	s_mov_b32 m0, s43
	s_nop 0
	global_load_lds_dwordx4 v[130:131], off
	v_lshl_add_u64 v[130:131], s[46:47], 0, v[154:155]
	s_add_i32 m0, s43, 0x2000
	s_nop 0
	global_load_lds_dwordx4 v[130:131], off
	s_waitcnt vmcnt(6)
	s_barrier
	v_mfma_f32_16x16x32_bf16 v[54:57], v[200:203], v[162:165], v[54:57]
	v_mfma_f32_16x16x32_bf16 v[46:49], v[208:211], v[162:165], v[46:49]
	v_mfma_f32_16x16x32_bf16 v[38:41], v[200:203], v[176:179], v[38:41]
	v_mfma_f32_16x16x32_bf16 v[30:33], v[208:211], v[176:179], v[30:33]
	v_mfma_f32_16x16x32_bf16 v[22:25], v[200:203], v[184:187], v[22:25]
	v_mfma_f32_16x16x32_bf16 v[14:17], v[208:211], v[184:187], v[14:17]
	v_mfma_f32_16x16x32_bf16 v[6:9], v[200:203], v[192:195], v[6:9]
	v_mfma_f32_16x16x32_bf16 v[2:5], v[208:211], v[192:195], v[2:5]
	v_mfma_f32_16x16x32_bf16 v[54:57], v[204:207], v[172:175], v[54:57]
	v_mfma_f32_16x16x32_bf16 v[46:49], v[212:215], v[172:175], v[46:49]
	v_mfma_f32_16x16x32_bf16 v[38:41], v[204:207], v[180:183], v[38:41]
	v_mfma_f32_16x16x32_bf16 v[30:33], v[212:215], v[180:183], v[30:33]
	v_mfma_f32_16x16x32_bf16 v[22:25], v[204:207], v[188:191], v[22:25]
	v_mfma_f32_16x16x32_bf16 v[14:17], v[212:215], v[188:191], v[14:17]
	v_mfma_f32_16x16x32_bf16 v[6:9], v[204:207], v[196:199], v[6:9]
	v_mfma_f32_16x16x32_bf16 v[2:5], v[212:215], v[196:199], v[2:5]
	s_add_i32 s41, s41, 2
	s_add_u32 s44, s44, 0x100
	s_addc_u32 s45, s45, 0
	s_add_u32 s2, s2, 0x100
	s_addc_u32 s3, s3, 0
	s_cmp_gt_u32 s41, 13
	s_barrier
	s_cbranch_scc0 .LBB0_281
	v_mov_b32_e32 v130, v147
	v_mov_b32_e32 v171, v1
	s_ashr_i32 s41, s66, 1
	s_mov_b64 s[48:49], -1
	v_lshlrev_b32_e32 v173, 3, v130
	s_mov_b64 s[46:47], 0
	s_cmp_lt_i32 s41, 4
	s_mov_b64 s[44:45], 0
	s_cbranch_scc1 .LBB0_297
	s_cmp_gt_i32 s41, 5
	s_cbranch_scc0 .LBB0_291
	s_cmp_gt_i32 s41, 6
	s_cbranch_scc0 .LBB0_288
	s_cmp_eq_u32 s41, 7
	s_mov_b64 s[44:45], -1
	s_cbranch_scc0 .LBB0_287
	s_lshl_b32 s2, s33, 8
	s_or_b32 s2, s2, s59
	v_add_u32_e32 v140, s2, v173
	v_add_u32_e32 v130, 0x8000, v140
	s_lshl_b32 s2, s66, 8
	v_ashrrev_i32_e32 v130, 3, v130
	s_and_b32 s2, s2, 0x100
	v_and_b32_e32 v130, 0xfffffe00, v130
	s_add_i32 s2, s2, s58
	v_add3_u32 v134, s2, v171, v130
	v_ashrrev_i32_e32 v135, 31, v134
	v_lshlrev_b64 v[136:137], 13, v[134:135]
	v_and_b32_e32 v135, 0xff8, v140
	v_lshl_add_u64 v[136:137], s[14:15], 0, v[136:137]
	v_lshlrev_b32_e32 v156, 1, v135
	v_cvt_pk_bf16_f32 v130, v126, v127
	v_cvt_pk_bf16_f32 v131, v128, v129
	v_cvt_pk_bf16_f32 v132, v122, v123
	v_cvt_pk_bf16_f32 v133, v124, v125
	v_lshl_add_u64 v[138:139], v[136:137], 0, v[156:157]
	global_store_dwordx4 v[138:139], v[130:133], off
	v_mov_b32_e32 v139, v157
	s_mov_b64 s[44:45], 0
	v_add_u32_e32 v130, 0x80, v140
	v_and_b32_e32 v135, 0xff8, v130
	v_lshlrev_b32_e32 v138, 1, v135
	v_cvt_pk_bf16_f32 v130, v118, v119
	v_cvt_pk_bf16_f32 v131, v120, v121
	v_cvt_pk_bf16_f32 v132, v110, v111
	v_cvt_pk_bf16_f32 v133, v112, v113
	v_lshl_add_u64 v[136:137], v[136:137], 0, v[138:139]
	global_store_dwordx4 v[136:137], v[130:133], off
	s_nop 1
	v_add_u32_e32 v130, 16, v134
	v_ashrrev_i32_e32 v131, 31, v130
	v_lshlrev_b64 v[136:137], 13, v[130:131]
	v_lshl_add_u64 v[136:137], s[14:15], 0, v[136:137]
	v_cvt_pk_bf16_f32 v130, v114, v115
	v_cvt_pk_bf16_f32 v131, v116, v117
	v_cvt_pk_bf16_f32 v132, v106, v107
	v_cvt_pk_bf16_f32 v133, v108, v109
	v_lshl_add_u64 v[140:141], v[136:137], 0, v[156:157]
	global_store_dwordx4 v[140:141], v[130:133], off
	v_lshl_add_u64 v[136:137], v[136:137], 0, v[138:139]
	s_nop 0
	v_cvt_pk_bf16_f32 v130, v102, v103
	v_cvt_pk_bf16_f32 v131, v104, v105
	v_cvt_pk_bf16_f32 v132, v94, v95
	v_cvt_pk_bf16_f32 v133, v96, v97
	global_store_dwordx4 v[136:137], v[130:133], off
	s_nop 1
	v_add_u32_e32 v130, 32, v134
	v_ashrrev_i32_e32 v131, 31, v130
	v_lshlrev_b64 v[136:137], 13, v[130:131]
	v_lshl_add_u64 v[136:137], s[14:15], 0, v[136:137]
	v_cvt_pk_bf16_f32 v130, v98, v99
	v_cvt_pk_bf16_f32 v131, v100, v101
	v_cvt_pk_bf16_f32 v132, v90, v91
	v_cvt_pk_bf16_f32 v133, v92, v93
	v_lshl_add_u64 v[140:141], v[136:137], 0, v[156:157]
	global_store_dwordx4 v[140:141], v[130:133], off
	v_lshl_add_u64 v[136:137], v[136:137], 0, v[138:139]
	s_nop 0
	v_cvt_pk_bf16_f32 v130, v86, v87
	v_cvt_pk_bf16_f32 v131, v88, v89
	v_cvt_pk_bf16_f32 v132, v78, v79
	v_cvt_pk_bf16_f32 v133, v80, v81
	global_store_dwordx4 v[136:137], v[130:133], off
	s_nop 1
	v_add_u32_e32 v130, 48, v134
	v_ashrrev_i32_e32 v131, 31, v130
	v_lshlrev_b64 v[136:137], 13, v[130:131]
	v_lshl_add_u64 v[136:137], s[14:15], 0, v[136:137]
	v_cvt_pk_bf16_f32 v130, v82, v83
	v_cvt_pk_bf16_f32 v131, v84, v85
	v_cvt_pk_bf16_f32 v132, v74, v75
	v_cvt_pk_bf16_f32 v133, v76, v77
	v_lshl_add_u64 v[140:141], v[136:137], 0, v[156:157]
	global_store_dwordx4 v[140:141], v[130:133], off
	v_lshl_add_u64 v[136:137], v[136:137], 0, v[138:139]
	s_nop 0
	v_cvt_pk_bf16_f32 v130, v70, v71
	v_cvt_pk_bf16_f32 v131, v72, v73
	v_cvt_pk_bf16_f32 v132, v66, v67
	v_cvt_pk_bf16_f32 v133, v68, v69
	global_store_dwordx4 v[136:137], v[130:133], off
	s_nop 1
	v_add_u32_e32 v130, 0x80, v134
	v_ashrrev_i32_e32 v131, 31, v130
	v_lshlrev_b64 v[136:137], 13, v[130:131]
	v_lshl_add_u64 v[136:137], s[14:15], 0, v[136:137]
	v_cvt_pk_bf16_f32 v130, v62, v63
	v_cvt_pk_bf16_f32 v131, v64, v65
	v_cvt_pk_bf16_f32 v132, v58, v59
	v_cvt_pk_bf16_f32 v133, v60, v61
	v_lshl_add_u64 v[140:141], v[136:137], 0, v[156:157]
	global_store_dwordx4 v[140:141], v[130:133], off
	v_lshl_add_u64 v[136:137], v[136:137], 0, v[138:139]
	s_nop 0
	v_cvt_pk_bf16_f32 v130, v54, v55
	v_cvt_pk_bf16_f32 v131, v56, v57
	v_cvt_pk_bf16_f32 v132, v46, v47
	v_cvt_pk_bf16_f32 v133, v48, v49
	global_store_dwordx4 v[136:137], v[130:133], off
	s_nop 1
	v_add_u32_e32 v130, 0x90, v134
	v_ashrrev_i32_e32 v131, 31, v130
	v_lshlrev_b64 v[136:137], 13, v[130:131]
	v_lshl_add_u64 v[136:137], s[14:15], 0, v[136:137]
	v_cvt_pk_bf16_f32 v130, v50, v51
	v_cvt_pk_bf16_f32 v131, v52, v53
	v_cvt_pk_bf16_f32 v132, v42, v43
	v_cvt_pk_bf16_f32 v133, v44, v45
	v_lshl_add_u64 v[140:141], v[136:137], 0, v[156:157]
	global_store_dwordx4 v[140:141], v[130:133], off
	v_lshl_add_u64 v[136:137], v[136:137], 0, v[138:139]
	s_nop 0
	v_cvt_pk_bf16_f32 v130, v38, v39
	v_cvt_pk_bf16_f32 v131, v40, v41
	v_cvt_pk_bf16_f32 v132, v30, v31
	v_cvt_pk_bf16_f32 v133, v32, v33
	global_store_dwordx4 v[136:137], v[130:133], off
	s_nop 1
	v_add_u32_e32 v130, 0xa0, v134
	v_ashrrev_i32_e32 v131, 31, v130
	v_lshlrev_b64 v[136:137], 13, v[130:131]
	v_lshl_add_u64 v[136:137], s[14:15], 0, v[136:137]
	v_cvt_pk_bf16_f32 v130, v34, v35
	v_cvt_pk_bf16_f32 v131, v36, v37
	v_cvt_pk_bf16_f32 v132, v26, v27
	v_cvt_pk_bf16_f32 v133, v28, v29
	v_lshl_add_u64 v[140:141], v[136:137], 0, v[156:157]
	global_store_dwordx4 v[140:141], v[130:133], off
	v_lshl_add_u64 v[136:137], v[136:137], 0, v[138:139]
	s_nop 0
	v_cvt_pk_bf16_f32 v130, v22, v23
	v_cvt_pk_bf16_f32 v131, v24, v25
	v_cvt_pk_bf16_f32 v132, v14, v15
	v_cvt_pk_bf16_f32 v133, v16, v17
	global_store_dwordx4 v[136:137], v[130:133], off
	s_nop 1
	v_add_u32_e32 v130, 0xb0, v134
	v_ashrrev_i32_e32 v131, 31, v130
	v_lshlrev_b64 v[134:135], 13, v[130:131]
	v_lshl_add_u64 v[134:135], s[14:15], 0, v[134:135]
	v_cvt_pk_bf16_f32 v130, v18, v19
	v_cvt_pk_bf16_f32 v131, v20, v21
	v_cvt_pk_bf16_f32 v132, v10, v11
	v_cvt_pk_bf16_f32 v133, v12, v13
	v_lshl_add_u64 v[136:137], v[134:135], 0, v[156:157]
	global_store_dwordx4 v[136:137], v[130:133], off
	v_lshl_add_u64 v[134:135], v[134:135], 0, v[138:139]
	s_nop 0
	v_cvt_pk_bf16_f32 v130, v6, v7
	v_cvt_pk_bf16_f32 v131, v8, v9
	v_cvt_pk_bf16_f32 v132, v2, v3
	v_cvt_pk_bf16_f32 v133, v4, v5
	global_store_dwordx4 v[134:135], v[130:133], off
